# baseline (speedup 1.0000x reference)
; __device__ __forceinline__ void attn_block(const ABlk& cur, char* lds, ASeam& Sm, const int tid, const int wv) {
;     ...
;     for (int t = 1; t + 1 < NT; t += 2) {
;         HALF_STEP(pB0, pB1, mnB, alB, pA0, pA1, alA, t, 1, 0, 0);
;         HALF_STEP(pA0, pA1, mnA, alA, pB0, pB1, alB, t + 1, 0, 1, 1);
.Lhead_bar:
	s_barrier

; __device__ __forceinline__ void partialSM(f32x16& p0, f32x16& p1, float& m_reg, float& mn, float& alpha) {
;     float pmax = p0[0];
; #pragma unroll
;     for (int r = 1; r < 16; ++r) pmax = fmaxf(pmax, p0[r]);
; #pragma unroll
;     for (int r = 0; r < 16; ++r) pmax = fmaxf(pmax, p1[r]);
;     { auto rr = __builtin_amdgcn_permlane32_swap(__float_as_uint(pmax), __float_as_uint(pmax), false, false);
;       pmax = fmaxf(__uint_as_float(rr[0]), __uint_as_float(rr[1])); }
;     constexpr float C2 = 1.4426950408889634f * ASCALE;
;     if (__builtin_expect(__all((pmax - m_reg) * ASCALE <= ATHR), 1)) { mn = m_reg; alpha = 1.f; }
;     else { mn = fmaxf(m_reg, pmax); alpha = __builtin_amdgcn_exp2f((m_reg - mn) * C2); m_reg = mn; }
; template <int VB>
; __device__ __forceinline__ void pv_tile(f32x16* o, int vb0, bf16x8 pa0, bf16x8 pa1, bf16x8 pa2, bf16x8 pa3) {
;     ...
;     PV_D0(0); PV_D0(1); PV_D0(2); PV_D0(3);
.LBB0_410:
	s_nop 0
	s_waitcnt lgkmcnt(4)
	v_mfma_f32_32x32x16_bf16 v[50:65], v[166:169], v[214:217], v[50:65]
	ds_read_b64_tr_b16 v[214:215], v194 offset:0x200
	ds_read_b64_tr_b16 v[216:217], v194 offset:0xa00
	v_max_f32_e32 v0, v82, v83
	v_mfma_f32_32x32x16_bf16 v[50:65], v[170:173], v[218:221], v[50:65]
	ds_read_b64_tr_b16 v[218:219], v194 offset:0x1200
	ds_read_b64_tr_b16 v[220:221], v194 offset:0x1a00
	v_max3_f32 v0, v0, v84, v85
	v_max3_f32 v0, v0, v86, v87
	s_waitcnt lgkmcnt(4)
	v_mfma_f32_32x32x16_bf16 v[50:65], v[174:177], v[222:225], v[50:65]
	ds_read_b64_tr_b16 v[222:223], v194 offset:0x2200
	ds_read_b64_tr_b16 v[224:225], v194 offset:0x2a00
	v_max3_f32 v0, v0, v88, v89
	v_max3_f32 v0, v0, v90, v91
	v_mfma_f32_32x32x16_bf16 v[50:65], v[178:181], v[226:229], v[50:65]
	ds_read_b64_tr_b16 v[226:227], v194 offset:0x3200
	ds_read_b64_tr_b16 v[228:229], v194 offset:0x3a00
	v_max3_f32 v0, v0, v92, v93
	v_max3_f32 v0, v0, v94, v95
	v_max3_f32 v0, v0, v96, v97
	s_waitcnt lgkmcnt(4)
	v_mfma_f32_32x32x16_bf16 v[34:49], v[166:169], v[214:217], v[34:49]
	ds_read_b64_tr_b16 v[214:215], v194 offset:0x400
	ds_read_b64_tr_b16 v[216:217], v194 offset:0xc00
	v_max3_f32 v0, v0, v66, v67
	v_max3_f32 v0, v0, v68, v69
	v_mfma_f32_32x32x16_bf16 v[34:49], v[170:173], v[218:221], v[34:49]
	ds_read_b64_tr_b16 v[218:219], v194 offset:0x1400
	ds_read_b64_tr_b16 v[220:221], v194 offset:0x1c00
	v_max3_f32 v0, v0, v70, v71
	v_max3_f32 v0, v0, v72, v73
	s_waitcnt lgkmcnt(4)
	v_mfma_f32_32x32x16_bf16 v[34:49], v[174:177], v[222:225], v[34:49]
	ds_read_b64_tr_b16 v[222:223], v194 offset:0x2400
	ds_read_b64_tr_b16 v[224:225], v194 offset:0x2c00
	v_max3_f32 v0, v0, v74, v75
	v_max3_f32 v0, v0, v76, v77
	v_max3_f32 v0, v0, v78, v79
	v_mfma_f32_32x32x16_bf16 v[34:49], v[178:181], v[226:229], v[34:49]
	ds_read_b64_tr_b16 v[226:227], v194 offset:0x3400
	ds_read_b64_tr_b16 v[228:229], v194 offset:0x3c00
	v_max3_f32 v0, v0, v80, v81
	v_mov_b32_e32 v190, v0
	s_waitcnt lgkmcnt(4)
	v_mfma_f32_32x32x16_bf16 v[18:33], v[166:169], v[214:217], v[18:33]
	ds_read_b64_tr_b16 v[214:215], v194 offset:0x600
	ds_read_b64_tr_b16 v[216:217], v194 offset:0xe00
	v_permlane32_swap_b32_e32 v0, v190
	v_mfma_f32_32x32x16_bf16 v[18:33], v[170:173], v[218:221], v[18:33]
	ds_read_b64_tr_b16 v[218:219], v194 offset:0x1600
	ds_read_b64_tr_b16 v[220:221], v194 offset:0x1e00
	v_max_f32_e32 v0, v0, v190
	s_waitcnt lgkmcnt(4)
	v_mfma_f32_32x32x16_bf16 v[18:33], v[174:177], v[222:225], v[18:33]
	ds_read_b64_tr_b16 v[222:223], v194 offset:0x2600
	ds_read_b64_tr_b16 v[224:225], v194 offset:0x2e00
	v_sub_f32_e32 v190, v0, v210
	v_mfma_f32_32x32x16_bf16 v[18:33], v[178:181], v[226:229], v[18:33]
	ds_read_b64_tr_b16 v[226:227], v194 offset:0x3600
	ds_read_b64_tr_b16 v[228:229], v194 offset:0x3e00
	v_max_f32_e32 v0, v210, v0
	v_sub_f32_e32 v191, v210, v0
	s_waitcnt lgkmcnt(4)
	v_mfma_f32_32x32x16_bf16 v[2:17], v[166:169], v[214:217], v[2:17]
	s_waitcnt vmcnt(2)
	v_add_u32_e32 v192, 0x10800, v206
	ds_write_b128 v207, v[154:157] offset:32768
	ds_write_b128 v207, v[158:161] offset:41472
	ds_write_b128 v192, v[162:165]
	v_mul_f32_e32 v191, 0x3dd53b94, v191
	v_mul_f32_e32 v190, 0x3d93cd3a, v190
	v_exp_f32_e32 v191, v191
	v_mfma_f32_32x32x16_bf16 v[2:17], v[170:173], v[218:221], v[2:17]
	v_cmp_ge_f32_e32 vcc, 0x41000000, v190
	s_waitcnt lgkmcnt(3)
	v_mfma_f32_32x32x16_bf16 v[2:17], v[174:177], v[222:225], v[2:17]
	s_cmp_eq_u64 vcc, exec
	s_cselect_b64 s[6:7], -1, 0
	v_mfma_f32_32x32x16_bf16 v[2:17], v[178:181], v[226:229], v[2:17]
	s_barrier
	s_waitcnt vmcnt(0)
	v_cndmask_b32_e64 v213, v191, 1.0, s[6:7]
	v_cmp_gt_f32_e32 vcc, 1.0, v213
	ds_write_b128 v202, v[146:149]
	ds_write_b128 v203, v[150:153]
	s_cbranch_vccz .LBB0_414
	s_and_saveexec_b64 s[8:9], s[4:5]
	ds_write_b32 v195, v213 offset:128
	s_or_b64 exec, exec, s[8:9]
	s_waitcnt lgkmcnt(0)
	ds_read_b128 v[166:169], v198 offset:224
	ds_read_b128 v[170:173], v198 offset:192
	ds_read_b128 v[174:177], v198 offset:160
	ds_read_b128 v[178:181], v198 offset:128
	s_waitcnt lgkmcnt(3)
	v_pk_mul_f32 v[64:65], v[64:65], v[168:169]
	s_waitcnt lgkmcnt(2)
	v_pk_mul_f32 v[60:61], v[60:61], v[172:173]
	s_waitcnt lgkmcnt(1)
	v_pk_mul_f32 v[56:57], v[56:57], v[176:177]
	s_waitcnt lgkmcnt(0)
	v_pk_mul_f32 v[52:53], v[52:53], v[180:181]
	v_pk_mul_f32 v[62:63], v[62:63], v[166:167]
	v_pk_mul_f32 v[58:59], v[58:59], v[170:171]
	v_pk_mul_f32 v[54:55], v[54:55], v[174:175]
	v_pk_mul_f32 v[50:51], v[50:51], v[178:179]
	v_pk_mul_f32 v[48:49], v[48:49], v[168:169]
	v_pk_mul_f32 v[44:45], v[44:45], v[172:173]
	v_pk_mul_f32 v[40:41], v[40:41], v[176:177]
	v_pk_mul_f32 v[36:37], v[36:37], v[180:181]
	v_pk_mul_f32 v[46:47], v[46:47], v[166:167]
	v_pk_mul_f32 v[42:43], v[42:43], v[170:171]
	v_pk_mul_f32 v[38:39], v[38:39], v[174:175]
	v_pk_mul_f32 v[34:35], v[34:35], v[178:179]
	v_pk_mul_f32 v[32:33], v[32:33], v[168:169]
	v_pk_mul_f32 v[28:29], v[28:29], v[172:173]
	v_pk_mul_f32 v[24:25], v[24:25], v[176:177]
	v_pk_mul_f32 v[20:21], v[20:21], v[180:181]
	v_pk_mul_f32 v[30:31], v[30:31], v[166:167]
	v_pk_mul_f32 v[26:27], v[26:27], v[170:171]
	v_pk_mul_f32 v[22:23], v[22:23], v[174:175]
	v_pk_mul_f32 v[18:19], v[18:19], v[178:179]
	v_pk_mul_f32 v[16:17], v[16:17], v[168:169]
	v_pk_mul_f32 v[12:13], v[12:13], v[172:173]
	v_pk_mul_f32 v[8:9], v[8:9], v[176:177]
	v_pk_mul_f32 v[4:5], v[4:5], v[180:181]
	v_pk_mul_f32 v[14:15], v[14:15], v[166:167]
	v_pk_mul_f32 v[10:11], v[10:11], v[170:171]
	v_pk_mul_f32 v[6:7], v[6:7], v[174:175]
	v_pk_mul_f32 v[2:3], v[2:3], v[178:179]

; __device__ __forceinline__ void partialSM(f32x16& p0, f32x16& p1, float& m_reg, float& mn, float& alpha) {
;     float pmax = p0[0];
; #pragma unroll
;     for (int r = 1; r < 16; ++r) pmax = fmaxf(pmax, p0[r]);
; #pragma unroll
;     for (int r = 0; r < 16; ++r) pmax = fmaxf(pmax, p1[r]);
;     { auto rr = __builtin_amdgcn_permlane32_swap(__float_as_uint(pmax), __float_as_uint(pmax), false, false);
;       pmax = fmaxf(__uint_as_float(rr[0]), __uint_as_float(rr[1])); }
;     constexpr float C2 = 1.4426950408889634f * ASCALE;
;     if (__builtin_expect(__all((pmax - m_reg) * ASCALE <= ATHR), 1)) { mn = m_reg; alpha = 1.f; }
;     else { mn = fmaxf(m_reg, pmax); alpha = __builtin_amdgcn_exp2f((m_reg - mn) * C2); m_reg = mn; }
.Lkw2_done:
	v_sub_f32_e32 v190, v0, v210
	v_mul_f32_e32 v190, 0x3d93cd3a, v190
	v_mfma_f32_32x32x16_bf16 v[2:17], v[170:173], v[222:225], v[2:17]
	v_cmp_ge_f32_e32 vcc, 0x41000000, v190
	s_waitcnt lgkmcnt(3)
	v_mfma_f32_32x32x16_bf16 v[2:17], v[174:177], v[226:229], v[2:17]
	s_cmp_eq_u64 vcc, exec
	s_cselect_b64 s[6:7], -1, 0
	v_mfma_f32_32x32x16_bf16 v[2:17], v[178:181], v[230:233], v[2:17]
	s_andn2_b64 vcc, exec, s[90:91]
	s_barrier
	s_cbranch_vccnz .LBB0_420
	s_waitcnt vmcnt(0)
	ds_write_b128 v202, v[146:149] offset:16384
	s_waitcnt vmcnt(0)
	ds_write_b128 v203, v[150:153] offset:16384

; __device__ __forceinline__ void partialSM(f32x16& p0, f32x16& p1, float& m_reg, float& mn, float& alpha) {
;     ...
;     const float mnL = -mn * C2;
; #pragma unroll
;     for (int r = 0; r < 16; ++r) p0[r] = fmaf(p0[r], C2, mnL);
; #pragma unroll
;     for (int r = 0; r < 16; ++r) p1[r] = fmaf(p1[r], C2, mnL);
; __device__ __forceinline__ void attn_block(const ABlk& cur, char* lds, ASeam& Sm, const int tid, const int wv) {
;     ...
;     for (int t = 1; t + 1 < NT; t += 2) {
;         HALF_STEP(pB0, pB1, mnB, alB, pA0, pA1, alA, t, 1, 0, 0);
;         HALF_STEP(pA0, pA1, mnA, alA, pB0, pB1, alB, t + 1, 0, 1, 1);
.LBB0_424:
	s_waitcnt vmcnt(0)
	v_cndmask_b32_e64 v210, v146, v210, s[6:7]
	v_mul_f32_e32 v148, 0xbdd53b94, v210
	s_addk_i32 s70, 0x80
	v_fmamk_f32 v166, v82, 0x3dd53b94, v148
	v_fmamk_f32 v175, v83, 0x3dd53b94, v148
	v_fmamk_f32 v167, v84, 0x3dd53b94, v148
	v_fmamk_f32 v176, v85, 0x3dd53b94, v148
	v_fmamk_f32 v168, v86, 0x3dd53b94, v148
	v_fmamk_f32 v177, v87, 0x3dd53b94, v148
	v_fmamk_f32 v169, v88, 0x3dd53b94, v148
	v_fmamk_f32 v174, v89, 0x3dd53b94, v148
	v_fmamk_f32 v165, v90, 0x3dd53b94, v148
	v_fmamk_f32 v170, v91, 0x3dd53b94, v148
	v_fmamk_f32 v171, v92, 0x3dd53b94, v148
	v_fmamk_f32 v172, v93, 0x3dd53b94, v148
	v_fmamk_f32 v162, v94, 0x3dd53b94, v148
	v_fmamk_f32 v164, v95, 0x3dd53b94, v148
	v_fmamk_f32 v163, v96, 0x3dd53b94, v148
	v_fmamk_f32 v173, v97, 0x3dd53b94, v148
	s_add_u32 s76, s76, 0x8000
	s_addc_u32 s77, s77, 0
	v_pk_fma_f32 v[160:161], v[66:67], s[84:85], v[148:149] op_sel_hi:[1,0,0]
	v_add_f32_e32 v66, v211, v212
	s_add_u32 s88, s88, 0x4000
	v_fmac_f32_e32 v66, v208, v196
	v_add_f32_e32 v196, v215, v216
	s_addc_u32 s89, s89, 0
	s_add_i32 s82, s82, 2
	v_pk_fma_f32 v[158:159], v[68:69], s[84:85], v[148:149] op_sel_hi:[1,0,0]
	v_pk_fma_f32 v[154:155], v[70:71], s[84:85], v[148:149] op_sel_hi:[1,0,0]
	v_pk_fma_f32 v[150:151], v[72:73], s[84:85], v[148:149] op_sel_hi:[1,0,0]
	v_pk_fma_f32 v[146:147], v[74:75], s[84:85], v[148:149] op_sel_hi:[1,0,0]
	v_pk_fma_f32 v[156:157], v[76:77], s[84:85], v[148:149] op_sel_hi:[1,0,0]
	v_pk_fma_f32 v[152:153], v[78:79], s[84:85], v[148:149] op_sel_hi:[1,0,0]
	v_pk_fma_f32 v[148:149], v[80:81], s[84:85], v[148:149] op_sel_hi:[1,0,0]
	v_fmac_f32_e32 v196, v66, v213
	s_cmp_ge_u32 s82, s83
	v_add_u32_e32 v209, 0xffffff80, v209
	v_mov_b32_e32 v208, v0
	s_waitcnt lgkmcnt(0)
	s_cbranch_scc1 .Lexit_bar
	s_branch .Lhead_bar
